# static s_setprio 1 for waves 0-3 (older half) instead of waves 4-7
# baseline (speedup 1.0000x reference)
; __device__ __forceinline__ int half_id() { return __builtin_amdgcn_readfirstlane((int)(threadIdx.x >> 8)); }
; __global__ void __launch_bounds__(512, 2) fwd_megakernel(Params p) {
;   cg::grid_group grid = cg::this_grid();
;   if (p.inv_freq[0] < 0.f) grid.sync();
_Z14fwd_megakernel6Params:
	v_readfirstlane_b32 s3, v0
	s_nop 3
	s_and_b32 s3, s3, 0x3ff
	s_lshr_b32 s3, s3, 8
	s_cmp_eq_u32 s3, 0
	s_cbranch_scc0 .Lprio_done
	s_setprio 1
